# p5d: 32 serialized K-row loads per item batched as rolling window of 16; plus weight-conversion tail filling
# speedup vs baseline: 1.0205x; 1.0170x over previous
; #define LAS __attribute__((address_space(3)))
; __global__ void __launch_bounds__(NTHREADS, 2) fwd_kernel(Params P) {
;     ...
;     const XcdBarrier gbar = xcd_barrier_post((unsigned*)(P.ws + WS_BAR), bst);
;     ...
;     if (PHON(0)) {
;         LAS float* scr = (LAS float*)(lds + wave * 16384);
;         constexpr int IT_GU = (D / 64) * (NZ / 32), IT_DN = (FF / 64) * (D / 32), IT_SQ = (D / 64) * (D / 32), IT_BR = (BW / 64) * (D / 32), IT_LR = 2 * 4;
;         constexpr int IT_TOTAL = 3 * IT_GU + 2 * IT_DN + 2 * IT_SQ + 3 * IT_BR + 16 * IT_LR;
;         for (int it = gw; it < IT_TOTAL; it += NGW) {
.LBB0_5:
	s_or_b64 exec, exec, s[4:5]
	s_load_dwordx16 s[8:23], s[0:1], 0x0
	s_lshl_b32 s86, s94, 3
	v_and_b32_e32 v237, 63, v178
	v_mbcnt_lo_u32_b32 v179, -1, 0
	s_waitcnt lgkmcnt(0)
	v_writelane_b32 v254, s8, 45
	s_nop 1
	v_writelane_b32 v254, s9, 46
	v_writelane_b32 v254, s10, 47
	v_writelane_b32 v254, s11, 48
	v_writelane_b32 v254, s12, 49
	v_writelane_b32 v254, s13, 50
	v_writelane_b32 v254, s14, 51
	v_writelane_b32 v254, s15, 52
	v_writelane_b32 v254, s16, 53
	v_writelane_b32 v254, s17, 54
	v_writelane_b32 v254, s18, 55
	v_writelane_b32 v254, s19, 56
	v_writelane_b32 v254, s20, 57
	v_writelane_b32 v254, s21, 58
	v_writelane_b32 v254, s22, 59
	v_writelane_b32 v254, s23, 60
	s_load_dwordx16 s[8:23], s[0:1], 0x80
	s_lshr_b32 s1, s37, 6
	s_lshl_b32 s0, s34, 3
	s_add_i32 s0, s1, s0
	s_mov_b32 s30, s0
	s_waitcnt lgkmcnt(0)
	v_writelane_b32 v254, s8, 61
	s_cmp_gt_i32 s0, 0xcc7f
	s_nop 0
	v_writelane_b32 v255, s11, 0
	v_writelane_b32 v255, s12, 1
	v_writelane_b32 v255, s13, 2
	v_writelane_b32 v255, s14, 3
	v_writelane_b32 v255, s15, 4
	v_writelane_b32 v255, s16, 5
	v_writelane_b32 v255, s17, 6
	v_writelane_b32 v255, s18, 7
	v_writelane_b32 v255, s19, 8
	v_writelane_b32 v255, s20, 9
	v_writelane_b32 v255, s21, 10
	v_writelane_b32 v255, s22, 11
	v_writelane_b32 v254, s9, 62
	v_writelane_b32 v255, s23, 12
	v_writelane_b32 v254, s10, 63
	v_writelane_b32 v255, s1, 13
	s_cbranch_scc1 .LBB0_62
	s_mov_b32 s100, 0
	s_mov_b32 s98, 0x2bff

; __global__ void __launch_bounds__(NTHREADS, 2) fwd_kernel(Params P) {
;     ...
;         for (int it = gw; it < IT_TOTAL; it += NGW) {
.Lcv_exit:
	s_cmp_lg_u32 s100, 0
	s_cbranch_scc1 .Lcv_d1
	s_mov_b32 s100, 1
	s_mov_b32 s98, 0x73ff
	v_readlane_b32 s99, v255, 13
	s_lshl_b32 s101, s34, 3
	s_nop 3
	s_add_i32 s99, s99, s101
	s_add_i32 s99, s99, 0x400
	s_and_b32 s99, s99, 0x7ff
	s_add_i32 s30, s99, 0x5800
	s_branch .Lcv_entry

; __device__ __forceinline__ float bflo(unsigned w) { return __uint_as_float(w << 16); }
; __device__ __forceinline__ float bfhi(unsigned w) { return __uint_as_float(w & 0xffff0000u); }
; __device__ __forceinline__ void p5d_sample_attn(const Params& P, LAS unsigned char* lds, int bid, int G, int tid_in) {
;     ...
;             const u32x2 qw = *(const u32x2*)(Z + (size_t)(MP + b) * NZ + 4096 + h * HD + 4 * lane);
;             const f32x4 q = (f32x4){bflo(qw.x), bfhi(qw.x), bflo(qw.y), bfhi(qw.y)};
;             const float* kbase = P.in[I_CK] + ((size_t)(b * NMEM + 32 * wave) * NH + h) * HD + 4 * lane;
;             const float* vbase = P.in[I_CV] + ((size_t)(b * NMEM + 32 * wave) * NH + h) * HD + 4 * lane;
;             float d[32];
; #pragma unroll
;             for (int mi = 0; mi < 32; ++mi) {
;                 const f32x4 kv = __builtin_nontemporal_load((const f32x4*)(kbase + (size_t)mi * (NH * HD)));
;                 d[mi] = (kv[0] * q[0] + kv[1] * q[1]) + (kv[2] * q[2] + kv[3] * q[3]);
;                 if (mi == 15) asm volatile("" ::: "memory");
;             }
.LBB0_565:
	s_ashr_i32 s18, s2, 2
	s_add_i32 s26, s18, 0x2000
	s_mul_i32 s1, s26, 0x5800
	s_mul_hi_i32 s0, s26, 0x5800
	s_add_u32 s1, s92, s1
	s_addc_u32 s19, s93, s0
	s_and_b32 s28, s23, 0x300
	s_lshl_b32 s27, s28, 1
	s_add_u32 s0, s1, s27
	s_addc_u32 s1, s19, 0
	v_lshl_add_u64 v[0:1], s[0:1], 0, v[130:131]
	s_mov_b32 s0, 0xeda2000
	v_add_co_u32_e32 v0, vcc, s0, v0
	s_lshl_b32 s0, s18, 8
	s_nop 0
	v_addc_co_u32_e32 v1, vcc, 0, v1, vcc
	global_load_dwordx2 v[0:1], v[0:1], off
	s_add_i32 s0, s0, s3
	s_ashr_i32 s1, s0, 31
	s_lshl_b64 s[0:1], s[0:1], 10
	s_or_b32 s0, s0, s28
	s_movk_i32 s18, 0x2000
	s_waitcnt vmcnt(0)
	v_lshlrev_b32_e32 v4, 16, v0
	v_and_b32_e32 v7, 0xffff0000, v0
	v_lshlrev_b32_e32 v5, 16, v1
	v_and_b32_e32 v6, 0xffff0000, v1
	v_lshl_add_u64 v[0:1], s[0:1], 2, v[132:133]
	global_load_dwordx4 v[184:187], v[0:1], off nt
	v_add_co_u32_e32 v168, vcc, 0x2000, v0
	s_nop 1
	v_addc_co_u32_e32 v169, vcc, 0, v1, vcc
	global_load_dwordx4 v[188:191], v[168:169], off offset:-4096 nt
	global_load_dwordx4 v[192:195], v[168:169], off nt
	v_add_co_u32_e32 v168, vcc, 0x4000, v0
	s_nop 1
	v_addc_co_u32_e32 v169, vcc, 0, v1, vcc
	global_load_dwordx4 v[196:199], v[168:169], off offset:-4096 nt
	global_load_dwordx4 v[200:203], v[168:169], off nt
	v_add_co_u32_e32 v168, vcc, 0x6000, v0
	s_nop 1
	v_addc_co_u32_e32 v169, vcc, 0, v1, vcc
	global_load_dwordx4 v[204:207], v[168:169], off offset:-4096 nt
	global_load_dwordx4 v[208:211], v[168:169], off nt
	v_add_co_u32_e32 v168, vcc, 0x8000, v0
	s_nop 1
	v_addc_co_u32_e32 v169, vcc, 0, v1, vcc
	global_load_dwordx4 v[212:215], v[168:169], off offset:-4096 nt
	global_load_dwordx4 v[216:219], v[168:169], off nt
	v_add_co_u32_e32 v168, vcc, 0xa000, v0
	s_nop 1
	v_addc_co_u32_e32 v169, vcc, 0, v1, vcc
	global_load_dwordx4 v[220:223], v[168:169], off offset:-4096 nt
	global_load_dwordx4 v[224:227], v[168:169], off nt
	v_add_co_u32_e32 v168, vcc, 0xc000, v0
	s_nop 1
	v_addc_co_u32_e32 v169, vcc, 0, v1, vcc
	global_load_dwordx4 v[228:231], v[168:169], off offset:-4096 nt
	global_load_dwordx4 v[238:241], v[168:169], off nt
	v_add_co_u32_e32 v168, vcc, 0xe000, v0
	s_nop 1
	v_addc_co_u32_e32 v169, vcc, 0, v1, vcc
	global_load_dwordx4 v[242:245], v[168:169], off offset:-4096 nt
	global_load_dwordx4 v[246:249], v[168:169], off nt
	v_add_co_u32_e32 v168, vcc, 0x10000, v0
	s_nop 1
	v_addc_co_u32_e32 v169, vcc, 0, v1, vcc
	global_load_dwordx4 v[250:253], v[168:169], off offset:-4096 nt
	s_waitcnt vmcnt(15)
	v_mul_f32_e32 v2, v185, v7
	v_mul_f32_e32 v3, v187, v6
	v_fmac_f32_e32 v2, v184, v4
	v_fmac_f32_e32 v3, v186, v5
	v_add_f32_e32 v8, v2, v3
	global_load_dwordx4 v[184:187], v[168:169], off nt
	v_add_co_u32_e32 v168, vcc, 0x12000, v0
	s_nop 1
	v_addc_co_u32_e32 v169, vcc, 0, v1, vcc
	s_waitcnt vmcnt(15)
	v_mul_f32_e32 v2, v189, v7
	v_mul_f32_e32 v3, v191, v6
	v_fmac_f32_e32 v2, v188, v4
	v_fmac_f32_e32 v3, v190, v5
	v_add_f32_e32 v9, v2, v3
	global_load_dwordx4 v[188:191], v[168:169], off offset:-4096 nt
	s_waitcnt vmcnt(15)
	v_mul_f32_e32 v2, v193, v7
	v_mul_f32_e32 v3, v195, v6
	v_fmac_f32_e32 v2, v192, v4
	v_fmac_f32_e32 v3, v194, v5
	v_add_f32_e32 v10, v2, v3
	global_load_dwordx4 v[192:195], v[168:169], off nt
	v_add_co_u32_e32 v168, vcc, 0x14000, v0
	s_nop 1
	v_addc_co_u32_e32 v169, vcc, 0, v1, vcc
	s_waitcnt vmcnt(15)
	v_mul_f32_e32 v2, v197, v7
	v_mul_f32_e32 v3, v199, v6
	v_fmac_f32_e32 v2, v196, v4
	v_fmac_f32_e32 v3, v198, v5
	v_add_f32_e32 v11, v2, v3
	global_load_dwordx4 v[196:199], v[168:169], off offset:-4096 nt
	s_waitcnt vmcnt(15)
	v_mul_f32_e32 v2, v201, v7
	v_mul_f32_e32 v3, v203, v6
	v_fmac_f32_e32 v2, v200, v4
	v_fmac_f32_e32 v3, v202, v5
	v_add_f32_e32 v12, v2, v3
	global_load_dwordx4 v[200:203], v[168:169], off nt
	v_add_co_u32_e32 v168, vcc, 0x16000, v0
	s_nop 1
	v_addc_co_u32_e32 v169, vcc, 0, v1, vcc
	s_waitcnt vmcnt(15)
	v_mul_f32_e32 v2, v205, v7
	v_mul_f32_e32 v3, v207, v6
	v_fmac_f32_e32 v2, v204, v4
	v_fmac_f32_e32 v3, v206, v5
	v_add_f32_e32 v14, v2, v3
	global_load_dwordx4 v[204:207], v[168:169], off offset:-4096 nt
	s_waitcnt vmcnt(15)
	v_mul_f32_e32 v2, v209, v7
	v_mul_f32_e32 v3, v211, v6
	v_fmac_f32_e32 v2, v208, v4
	v_fmac_f32_e32 v3, v210, v5
	v_add_f32_e32 v13, v2, v3
	global_load_dwordx4 v[208:211], v[168:169], off nt
	v_add_co_u32_e32 v168, vcc, 0x18000, v0
	s_nop 1
	v_addc_co_u32_e32 v169, vcc, 0, v1, vcc
	s_waitcnt vmcnt(15)
	v_mul_f32_e32 v2, v213, v7
	v_mul_f32_e32 v3, v215, v6
	v_fmac_f32_e32 v2, v212, v4
	v_fmac_f32_e32 v3, v214, v5
	v_add_f32_e32 v15, v2, v3
	global_load_dwordx4 v[212:215], v[168:169], off offset:-4096 nt
	s_waitcnt vmcnt(15)
	v_mul_f32_e32 v2, v217, v7
	v_mul_f32_e32 v3, v219, v6
	v_fmac_f32_e32 v2, v216, v4
	v_fmac_f32_e32 v3, v218, v5
	v_add_f32_e32 v16, v2, v3
	global_load_dwordx4 v[216:219], v[168:169], off nt
	v_add_co_u32_e32 v168, vcc, 0x1a000, v0
	s_nop 1
	v_addc_co_u32_e32 v169, vcc, 0, v1, vcc
	s_waitcnt vmcnt(15)
	v_mul_f32_e32 v2, v221, v7
	v_mul_f32_e32 v3, v223, v6
	v_fmac_f32_e32 v2, v220, v4
	v_fmac_f32_e32 v3, v222, v5
	v_add_f32_e32 v17, v2, v3
	global_load_dwordx4 v[220:223], v[168:169], off offset:-4096 nt
	s_waitcnt vmcnt(15)
	v_mul_f32_e32 v2, v225, v7
	v_mul_f32_e32 v3, v227, v6
	v_fmac_f32_e32 v2, v224, v4
	v_fmac_f32_e32 v3, v226, v5
	v_add_f32_e32 v18, v2, v3
	global_load_dwordx4 v[224:227], v[168:169], off nt
	v_add_co_u32_e32 v168, vcc, 0x1c000, v0
	s_nop 1
	v_addc_co_u32_e32 v169, vcc, 0, v1, vcc
	s_waitcnt vmcnt(15)
	v_mul_f32_e32 v2, v229, v7
	v_mul_f32_e32 v3, v231, v6
	v_fmac_f32_e32 v2, v228, v4
	v_fmac_f32_e32 v3, v230, v5
	v_add_f32_e32 v20, v2, v3
	global_load_dwordx4 v[228:231], v[168:169], off offset:-4096 nt
	s_waitcnt vmcnt(15)
; __device__ __forceinline__ void p5d_sample_attn(const Params& P, LAS unsigned char* lds, int bid, int G, int tid_in) {
;     ...
; #pragma unroll
;             for (int mi = 0; mi < 32; ++mi) {
;                 const f32x4 kv = __builtin_nontemporal_load((const f32x4*)(kbase + (size_t)mi * (NH * HD)));
;                 d[mi] = (kv[0] * q[0] + kv[1] * q[1]) + (kv[2] * q[2] + kv[3] * q[3]);
;                 if (mi == 15) asm volatile("" ::: "memory");
;             }
; #pragma unroll
;             for (int i = 0; i < 16; ++i) { const bool hi = (lane & 32) != 0; const float snd = hi ? d[i] : d[i + 16], kp = hi ? d[i + 16] : d[i]; d[i] = kp + __shfl_xor(snd, 32); }
	v_mul_f32_e32 v2, v239, v7
	v_mul_f32_e32 v3, v241, v6
	v_fmac_f32_e32 v2, v238, v4
	v_fmac_f32_e32 v3, v240, v5
	v_add_f32_e32 v19, v2, v3
	global_load_dwordx4 v[238:241], v[168:169], off nt
	v_add_co_u32_e32 v168, vcc, 0x1e000, v0
	s_nop 1
	v_addc_co_u32_e32 v169, vcc, 0, v1, vcc
	s_waitcnt vmcnt(15)
	v_mul_f32_e32 v2, v243, v7
	v_mul_f32_e32 v3, v245, v6
	v_fmac_f32_e32 v2, v242, v4
	v_fmac_f32_e32 v3, v244, v5
	v_add_f32_e32 v21, v2, v3
	global_load_dwordx4 v[242:245], v[168:169], off offset:-4096 nt
	s_waitcnt vmcnt(15)
	v_mul_f32_e32 v2, v247, v7
	v_mul_f32_e32 v3, v249, v6
	v_fmac_f32_e32 v2, v246, v4
	v_fmac_f32_e32 v3, v248, v5
	v_add_f32_e32 v22, v2, v3
	global_load_dwordx4 v[246:249], v[168:169], off nt
	v_add_co_u32_e32 v168, vcc, 0x20000, v0
	s_nop 1
	v_addc_co_u32_e32 v169, vcc, 0, v1, vcc
	s_waitcnt vmcnt(15)
	v_mul_f32_e32 v2, v251, v7
	v_mul_f32_e32 v3, v253, v6
	v_fmac_f32_e32 v2, v250, v4
	v_fmac_f32_e32 v3, v252, v5
	v_add_f32_e32 v23, v2, v3
	global_load_dwordx4 v[250:253], v[168:169], off offset:-4096 nt
	v_cmp_lt_i32_e32 vcc, v141, v142
	s_waitcnt vmcnt(15)
	v_mul_f32_e32 v2, v185, v7
	v_mul_f32_e32 v3, v187, v6
	v_fmac_f32_e32 v2, v184, v4
	v_fmac_f32_e32 v3, v186, v5
	v_add_f32_e32 v24, v2, v3
	s_waitcnt vmcnt(14)
	v_mul_f32_e32 v2, v189, v7
	v_mul_f32_e32 v3, v191, v6
	v_fmac_f32_e32 v2, v188, v4
	v_fmac_f32_e32 v3, v190, v5
	v_add_f32_e32 v25, v2, v3
	s_waitcnt vmcnt(13)
	v_mul_f32_e32 v2, v193, v7
	v_mul_f32_e32 v3, v195, v6
	v_fmac_f32_e32 v2, v192, v4
	v_fmac_f32_e32 v3, v194, v5
	v_add_f32_e32 v26, v2, v3
	s_waitcnt vmcnt(12)
	v_mul_f32_e32 v2, v197, v7
	v_mul_f32_e32 v3, v199, v6
	v_fmac_f32_e32 v2, v196, v4
	v_fmac_f32_e32 v3, v198, v5
	v_add_f32_e32 v27, v2, v3
	s_waitcnt vmcnt(11)
	v_mul_f32_e32 v2, v201, v7
	v_mul_f32_e32 v3, v203, v6
	v_fmac_f32_e32 v2, v200, v4
	v_fmac_f32_e32 v3, v202, v5
	v_add_f32_e32 v28, v2, v3
	s_waitcnt vmcnt(10)
	v_mul_f32_e32 v2, v205, v7
	v_mul_f32_e32 v3, v207, v6
	v_fmac_f32_e32 v2, v204, v4
	v_fmac_f32_e32 v3, v206, v5
	v_add_f32_e32 v29, v2, v3
	s_waitcnt vmcnt(9)
	v_mul_f32_e32 v2, v209, v7
	v_mul_f32_e32 v3, v211, v6
	v_fmac_f32_e32 v2, v208, v4
	v_fmac_f32_e32 v3, v210, v5
	v_add_f32_e32 v30, v2, v3
	s_waitcnt vmcnt(8)
	v_mul_f32_e32 v2, v213, v7
	v_mul_f32_e32 v3, v215, v6
	v_fmac_f32_e32 v2, v212, v4
	v_fmac_f32_e32 v3, v214, v5
	v_add_f32_e32 v31, v2, v3
	s_waitcnt vmcnt(7)
	v_mul_f32_e32 v2, v217, v7
	v_mul_f32_e32 v3, v219, v6
	v_fmac_f32_e32 v2, v216, v4
	v_fmac_f32_e32 v3, v218, v5
	v_add_f32_e32 v32, v2, v3
	s_waitcnt vmcnt(6)
	v_mul_f32_e32 v2, v221, v7
	v_mul_f32_e32 v3, v223, v6
	v_fmac_f32_e32 v2, v220, v4
	v_fmac_f32_e32 v3, v222, v5
	v_add_f32_e32 v33, v2, v3
	s_waitcnt vmcnt(5)
	v_mul_f32_e32 v2, v225, v7
	v_mul_f32_e32 v3, v227, v6
	v_fmac_f32_e32 v2, v224, v4
	v_fmac_f32_e32 v3, v226, v5
	v_add_f32_e32 v34, v2, v3
	s_waitcnt vmcnt(4)
	v_mul_f32_e32 v2, v229, v7
	v_mul_f32_e32 v3, v231, v6
	v_fmac_f32_e32 v2, v228, v4
	v_fmac_f32_e32 v3, v230, v5
	v_add_f32_e32 v35, v2, v3
	s_waitcnt vmcnt(3)
	v_mul_f32_e32 v2, v239, v7
	v_mul_f32_e32 v3, v241, v6
	v_fmac_f32_e32 v2, v238, v4
	v_fmac_f32_e32 v3, v240, v5
	v_add_f32_e32 v36, v2, v3
	s_waitcnt vmcnt(2)
	v_mul_f32_e32 v2, v243, v7
	v_mul_f32_e32 v3, v245, v6
	v_fmac_f32_e32 v2, v242, v4
	v_fmac_f32_e32 v3, v244, v5
	v_add_f32_e32 v37, v2, v3
	s_waitcnt vmcnt(1)
	v_mul_f32_e32 v2, v247, v7
	v_mul_f32_e32 v3, v249, v6
	v_fmac_f32_e32 v2, v246, v4
	v_fmac_f32_e32 v3, v248, v5
	v_add_f32_e32 v38, v2, v3
	s_waitcnt vmcnt(0)
	v_mul_f32_e32 v2, v251, v7
	v_mul_f32_e32 v3, v253, v6
	v_fmac_f32_e32 v2, v250, v4
	v_fmac_f32_e32 v3, v252, v5
	v_add_f32_e32 v1, v2, v3
	v_cndmask_b32_e32 v0, v140, v141, vcc
	v_lshlrev_b32_e32 v0, 2, v0
	v_cndmask_b32_e64 v2, v8, v24, s[4:5]
	ds_bpermute_b32 v2, v0, v2
	v_cndmask_b32_e64 v3, v24, v8, s[4:5]
	v_cndmask_b32_e64 v4, v25, v9, s[4:5]
	v_cndmask_b32_e64 v5, v26, v10, s[4:5]
	v_cndmask_b32_e64 v6, v27, v11, s[4:5]
	s_waitcnt lgkmcnt(0)
	v_add_f32_e32 v2, v3, v2
	v_cndmask_b32_e64 v3, v9, v25, s[4:5]
	ds_bpermute_b32 v3, v0, v3
	v_cndmask_b32_e64 v7, v28, v12, s[4:5]
	v_cndmask_b32_e64 v8, v29, v14, s[4:5]
	v_cndmask_b32_e64 v9, v30, v13, s[4:5]
	v_cmp_lt_i32_e32 vcc, v143, v142
	s_waitcnt lgkmcnt(0)
	v_add_f32_e32 v3, v4, v3
	v_cndmask_b32_e64 v4, v10, v26, s[4:5]
	ds_bpermute_b32 v4, v0, v4
	v_cndmask_b32_e64 v10, v31, v15, s[4:5]
	s_waitcnt lgkmcnt(0)
	v_add_f32_e32 v4, v5, v4
	v_cndmask_b32_e64 v5, v11, v27, s[4:5]
	ds_bpermute_b32 v5, v0, v5
	v_cndmask_b32_e64 v11, v32, v16, s[4:5]
	s_waitcnt lgkmcnt(0)
	v_add_f32_e32 v5, v6, v5
	v_cndmask_b32_e64 v6, v12, v28, s[4:5]
	ds_bpermute_b32 v6, v0, v6
	v_cndmask_b32_e64 v12, v33, v17, s[4:5]
	s_waitcnt lgkmcnt(0)
; __device__ __forceinline__ void p5d_sample_attn(const Params& P, LAS unsigned char* lds, int bid, int G, int tid_in) {
;     ...
;             for (int i = 0; i < 16; ++i) { const bool hi = (lane & 32) != 0; const float snd = hi ? d[i] : d[i + 16], kp = hi ? d[i + 16] : d[i]; d[i] = kp + __shfl_xor(snd, 32); }
; #pragma unroll
;             for (int i = 0; i < 8; ++i) { const bool hi = (lane & 16) != 0; const float snd = hi ? d[i] : d[i + 8], kp = hi ? d[i + 8] : d[i]; d[i] = kp + __shfl_xor(snd, 16); }
; #pragma unroll
;             for (int i = 0; i < 4; ++i) { const bool hi = (lane & 8) != 0; const float snd = hi ? d[i] : d[i + 4], kp = hi ? d[i + 4] : d[i]; d[i] = kp + __shfl_xor(snd, 8); }
; #pragma unroll
;             for (int i = 0; i < 2; ++i) { const bool hi = (lane & 4) != 0; const float snd = hi ? d[i] : d[i + 2], kp = hi ? d[i + 2] : d[i]; d[i] = kp + __shfl_xor(snd, 4); }
;             { const bool hi = (lane & 2) != 0; const float snd = hi ? d[0] : d[1], kp = hi ? d[1] : d[0]; d[0] = kp + __shfl_xor(snd, 2); }
;             d[0] += __shfl_xor(d[0], 1);
;             if ((lane & 1) == 0) sS[32 * wave + (lane >> 1)] = d[0] * 0.0625f;
	v_add_f32_e32 v6, v7, v6
	v_cndmask_b32_e64 v7, v14, v29, s[4:5]
	ds_bpermute_b32 v7, v0, v7
	v_cndmask_b32_e64 v14, v35, v20, s[4:5]
	s_waitcnt lgkmcnt(0)
	v_add_f32_e32 v7, v8, v7
	v_cndmask_b32_e64 v8, v13, v30, s[4:5]
	ds_bpermute_b32 v8, v0, v8
	v_cndmask_b32_e64 v13, v34, v18, s[4:5]
	s_waitcnt lgkmcnt(0)
	v_add_f32_e32 v8, v9, v8
	v_cndmask_b32_e64 v9, v15, v31, s[4:5]
	ds_bpermute_b32 v9, v0, v9
	v_cndmask_b32_e64 v15, v36, v19, s[4:5]
	s_waitcnt lgkmcnt(0)
	v_add_f32_e32 v9, v10, v9
	v_cndmask_b32_e64 v10, v16, v32, s[4:5]
	ds_bpermute_b32 v10, v0, v10
	v_cndmask_b32_e64 v16, v37, v21, s[4:5]
	s_waitcnt lgkmcnt(0)
	v_add_f32_e32 v10, v11, v10
	v_cndmask_b32_e64 v11, v17, v33, s[4:5]
	ds_bpermute_b32 v11, v0, v11
	v_cndmask_b32_e64 v17, v38, v22, s[4:5]
	s_waitcnt lgkmcnt(0)
	v_add_f32_e32 v11, v12, v11
	v_cndmask_b32_e64 v12, v18, v34, s[4:5]
	ds_bpermute_b32 v12, v0, v12
	v_cndmask_b32_e64 v18, v2, v10, s[6:7]
	v_cndmask_b32_e64 v2, v10, v2, s[6:7]
	s_waitcnt lgkmcnt(0)
	v_add_f32_e32 v12, v13, v12
	v_cndmask_b32_e64 v13, v20, v35, s[4:5]
	ds_bpermute_b32 v13, v0, v13
	s_waitcnt lgkmcnt(0)
	v_add_f32_e32 v13, v14, v13
	v_cndmask_b32_e64 v14, v19, v36, s[4:5]
	ds_bpermute_b32 v14, v0, v14
	s_waitcnt lgkmcnt(0)
	v_add_f32_e32 v14, v15, v14
	v_cndmask_b32_e64 v15, v21, v37, s[4:5]
	ds_bpermute_b32 v15, v0, v15
	s_waitcnt lgkmcnt(0)
	v_add_f32_e32 v15, v16, v15
	v_cndmask_b32_e64 v16, v22, v38, s[4:5]
	ds_bpermute_b32 v16, v0, v16
	s_waitcnt lgkmcnt(0)
	v_add_f32_e32 v16, v17, v16
	v_cndmask_b32_e64 v17, v23, v1, s[4:5]
	ds_bpermute_b32 v17, v0, v17
	v_cndmask_b32_e64 v1, v1, v23, s[4:5]
	s_waitcnt lgkmcnt(0)
	v_add_f32_e32 v17, v1, v17
	v_cndmask_b32_e32 v1, v140, v143, vcc
	v_lshlrev_b32_e32 v1, 2, v1
	ds_bpermute_b32 v10, v1, v18
	v_cmp_lt_i32_e32 vcc, v144, v142
	s_waitcnt lgkmcnt(0)
	v_add_f32_e32 v10, v2, v10
	v_cndmask_b32_e64 v2, v3, v11, s[6:7]
	ds_bpermute_b32 v2, v1, v2
	v_cndmask_b32_e64 v3, v11, v3, s[6:7]
	s_waitcnt lgkmcnt(0)
	v_add_f32_e32 v3, v3, v2
	v_cndmask_b32_e64 v2, v4, v12, s[6:7]
	ds_bpermute_b32 v2, v1, v2
	v_cndmask_b32_e64 v4, v12, v4, s[6:7]
	s_waitcnt lgkmcnt(0)
	v_add_f32_e32 v4, v4, v2
	v_cndmask_b32_e64 v2, v5, v13, s[6:7]
	ds_bpermute_b32 v2, v1, v2
	v_cndmask_b32_e64 v5, v13, v5, s[6:7]
	s_waitcnt lgkmcnt(0)
	v_add_f32_e32 v5, v5, v2
	v_cndmask_b32_e64 v2, v6, v14, s[6:7]
	ds_bpermute_b32 v2, v1, v2
	v_cndmask_b32_e64 v6, v14, v6, s[6:7]
	s_waitcnt lgkmcnt(0)
	v_add_f32_e32 v6, v6, v2
	v_cndmask_b32_e64 v2, v7, v15, s[6:7]
	ds_bpermute_b32 v2, v1, v2
	v_cndmask_b32_e64 v7, v15, v7, s[6:7]
	v_cndmask_b32_e64 v11, v10, v6, s[8:9]
	v_cndmask_b32_e64 v6, v6, v10, s[8:9]
	s_waitcnt lgkmcnt(0)
	v_add_f32_e32 v7, v7, v2
	v_cndmask_b32_e64 v2, v8, v16, s[6:7]
	ds_bpermute_b32 v2, v1, v2
	v_cndmask_b32_e64 v8, v16, v8, s[6:7]
	s_waitcnt lgkmcnt(0)
	v_add_f32_e32 v8, v8, v2
	v_cndmask_b32_e64 v2, v9, v17, s[6:7]
	ds_bpermute_b32 v2, v1, v2
	v_cndmask_b32_e64 v9, v17, v9, s[6:7]
	s_waitcnt lgkmcnt(0)
	v_add_f32_e32 v9, v9, v2
	v_cndmask_b32_e32 v2, v140, v144, vcc
	v_lshlrev_b32_e32 v2, 2, v2
	ds_bpermute_b32 v10, v2, v11
	v_cmp_lt_i32_e32 vcc, v145, v142
	s_waitcnt lgkmcnt(0)
	v_add_f32_e32 v6, v6, v10
	v_cndmask_b32_e64 v10, v3, v7, s[8:9]
	v_cndmask_b32_e64 v3, v7, v3, s[8:9]
	ds_bpermute_b32 v7, v2, v10
	s_waitcnt lgkmcnt(0)
	v_add_f32_e32 v7, v3, v7
	v_cndmask_b32_e64 v3, v4, v8, s[8:9]
	ds_bpermute_b32 v3, v2, v3
	v_cndmask_b32_e64 v4, v8, v4, s[8:9]
	s_waitcnt lgkmcnt(0)
	v_add_f32_e32 v4, v4, v3
	v_cndmask_b32_e64 v3, v5, v9, s[8:9]
	ds_bpermute_b32 v3, v2, v3
	v_cndmask_b32_e64 v5, v9, v5, s[8:9]
	v_cndmask_b32_e64 v8, v6, v4, s[10:11]
	v_cndmask_b32_e64 v4, v4, v6, s[10:11]
	s_waitcnt lgkmcnt(0)
	v_add_f32_e32 v5, v5, v3
	v_cndmask_b32_e32 v3, v140, v145, vcc
	v_lshlrev_b32_e32 v3, 2, v3
	ds_bpermute_b32 v6, v3, v8
	v_cmp_lt_i32_e32 vcc, v146, v142
	s_waitcnt lgkmcnt(0)
	v_add_f32_e32 v4, v4, v6
	v_cndmask_b32_e64 v6, v7, v5, s[10:11]
	ds_bpermute_b32 v6, v3, v6
	v_cndmask_b32_e64 v5, v5, v7, s[10:11]
	s_waitcnt lgkmcnt(0)
	v_add_f32_e32 v5, v5, v6
	v_cndmask_b32_e64 v6, v4, v5, s[12:13]
	v_cndmask_b32_e64 v5, v5, v4, s[12:13]
	v_cndmask_b32_e32 v4, v140, v146, vcc
	v_lshlrev_b32_e32 v4, 2, v4
	ds_bpermute_b32 v6, v4, v6
	v_cmp_lt_i32_e32 vcc, v147, v142
	s_waitcnt lgkmcnt(0)
	v_add_f32_e32 v6, v5, v6
	v_cndmask_b32_e32 v5, v140, v147, vcc
	v_lshlrev_b32_e32 v5, 2, v5
	ds_bpermute_b32 v7, v5, v6
	s_and_saveexec_b64 s[18:19], s[14:15]
	s_cbranch_execz .LBB0_567
	s_waitcnt lgkmcnt(0)
	v_add_f32_e32 v6, v6, v7
	v_mul_f32_e32 v6, 0x3d800000, v6
	ds_write_b32 v136, v6

; __device__ __forceinline__ float bflo(unsigned w) { return __uint_as_float(w << 16); }
; __device__ __forceinline__ float bfhi(unsigned w) { return __uint_as_float(w & 0xffff0000u); }
; __device__ __forceinline__ void p5d_sample_attn(const Params& P, LAS unsigned char* lds, int bid, int G, int tid_in) {
;     ...
;             const u32x2 qw = *(const u32x2*)(Z + (size_t)(MP + b) * NZ + 4096 + h * HD + 4 * lane);
;             const f32x4 q = (f32x4){bflo(qw.x), bfhi(qw.x), bflo(qw.y), bfhi(qw.y)};
;             const float* kbase = P.in[I_CK] + ((size_t)(b * NMEM + 32 * wave) * NH + h) * HD + 4 * lane;
;             const float* vbase = P.in[I_CV] + ((size_t)(b * NMEM + 32 * wave) * NH + h) * HD + 4 * lane;
;             float d[32];
; #pragma unroll
;             for (int mi = 0; mi < 32; ++mi) {
;                 const f32x4 kv = __builtin_nontemporal_load((const f32x4*)(kbase + (size_t)mi * (NH * HD)));
;                 d[mi] = (kv[0] * q[0] + kv[1] * q[1]) + (kv[2] * q[2] + kv[3] * q[3]);
;                 if (mi == 15) asm volatile("" ::: "memory");
;             }
.LBB0_637:
	s_ashr_i32 s18, s2, 2
	s_add_i32 s37, s18, 0x2000
	s_mul_i32 s1, s37, 0x5800
	s_mul_hi_i32 s0, s37, 0x5800
	s_add_u32 s1, s92, s1
	s_addc_u32 s19, s93, s0
	s_and_b32 s43, s23, 0x300
	s_lshl_b32 s42, s43, 1
	s_add_u32 s0, s1, s42
	s_addc_u32 s1, s19, 0
	v_lshl_add_u64 v[0:1], s[0:1], 0, v[130:131]
	s_mov_b32 s0, 0xeda2000
	v_add_co_u32_e32 v0, vcc, s0, v0
	s_lshl_b32 s0, s18, 8
	s_nop 0
	v_addc_co_u32_e32 v1, vcc, 0, v1, vcc
	global_load_dwordx2 v[0:1], v[0:1], off
	s_add_i32 s0, s0, s3
	s_ashr_i32 s1, s0, 31
	s_lshl_b64 s[0:1], s[0:1], 10
	s_or_b32 s0, s0, s43
	s_movk_i32 s18, 0x2000
	s_waitcnt vmcnt(0)
	v_lshlrev_b32_e32 v4, 16, v0
	v_and_b32_e32 v7, 0xffff0000, v0
	v_lshlrev_b32_e32 v5, 16, v1
	v_and_b32_e32 v6, 0xffff0000, v1
	v_lshl_add_u64 v[0:1], s[0:1], 2, v[132:133]
	global_load_dwordx4 v[184:187], v[0:1], off nt
	v_add_co_u32_e32 v168, vcc, 0x2000, v0
	s_nop 1
	v_addc_co_u32_e32 v169, vcc, 0, v1, vcc
	global_load_dwordx4 v[188:191], v[168:169], off offset:-4096 nt
	global_load_dwordx4 v[192:195], v[168:169], off nt
	v_add_co_u32_e32 v168, vcc, 0x4000, v0
	s_nop 1
	v_addc_co_u32_e32 v169, vcc, 0, v1, vcc
	global_load_dwordx4 v[196:199], v[168:169], off offset:-4096 nt
	global_load_dwordx4 v[200:203], v[168:169], off nt
	v_add_co_u32_e32 v168, vcc, 0x6000, v0
	s_nop 1
	v_addc_co_u32_e32 v169, vcc, 0, v1, vcc
	global_load_dwordx4 v[204:207], v[168:169], off offset:-4096 nt
	global_load_dwordx4 v[208:211], v[168:169], off nt
	v_add_co_u32_e32 v168, vcc, 0x8000, v0
	s_nop 1
	v_addc_co_u32_e32 v169, vcc, 0, v1, vcc
	global_load_dwordx4 v[212:215], v[168:169], off offset:-4096 nt
	global_load_dwordx4 v[216:219], v[168:169], off nt
	v_add_co_u32_e32 v168, vcc, 0xa000, v0
	s_nop 1
	v_addc_co_u32_e32 v169, vcc, 0, v1, vcc
	global_load_dwordx4 v[220:223], v[168:169], off offset:-4096 nt
	global_load_dwordx4 v[224:227], v[168:169], off nt
	v_add_co_u32_e32 v168, vcc, 0xc000, v0
	s_nop 1
	v_addc_co_u32_e32 v169, vcc, 0, v1, vcc
	global_load_dwordx4 v[228:231], v[168:169], off offset:-4096 nt
	global_load_dwordx4 v[238:241], v[168:169], off nt
	v_add_co_u32_e32 v168, vcc, 0xe000, v0
	s_nop 1
	v_addc_co_u32_e32 v169, vcc, 0, v1, vcc
	global_load_dwordx4 v[242:245], v[168:169], off offset:-4096 nt
	global_load_dwordx4 v[246:249], v[168:169], off nt
	v_add_co_u32_e32 v168, vcc, 0x10000, v0
	s_nop 1
	v_addc_co_u32_e32 v169, vcc, 0, v1, vcc
	global_load_dwordx4 v[250:253], v[168:169], off offset:-4096 nt
	s_waitcnt vmcnt(15)
	v_mul_f32_e32 v2, v185, v7
	v_mul_f32_e32 v3, v187, v6
	v_fmac_f32_e32 v2, v184, v4
	v_fmac_f32_e32 v3, v186, v5
	v_add_f32_e32 v8, v2, v3
	global_load_dwordx4 v[184:187], v[168:169], off nt
	v_add_co_u32_e32 v168, vcc, 0x12000, v0
	s_nop 1
	v_addc_co_u32_e32 v169, vcc, 0, v1, vcc
	s_waitcnt vmcnt(15)
	v_mul_f32_e32 v2, v189, v7
	v_mul_f32_e32 v3, v191, v6
	v_fmac_f32_e32 v2, v188, v4
	v_fmac_f32_e32 v3, v190, v5
	v_add_f32_e32 v10, v2, v3
	global_load_dwordx4 v[188:191], v[168:169], off offset:-4096 nt
	s_waitcnt vmcnt(15)
	v_mul_f32_e32 v2, v193, v7
	v_mul_f32_e32 v3, v195, v6
	v_fmac_f32_e32 v2, v192, v4
	v_fmac_f32_e32 v3, v194, v5
	v_add_f32_e32 v9, v2, v3
	global_load_dwordx4 v[192:195], v[168:169], off nt
	v_add_co_u32_e32 v168, vcc, 0x14000, v0
	s_nop 1
	v_addc_co_u32_e32 v169, vcc, 0, v1, vcc
	s_waitcnt vmcnt(15)
	v_mul_f32_e32 v2, v197, v7
	v_mul_f32_e32 v3, v199, v6
	v_fmac_f32_e32 v2, v196, v4
	v_fmac_f32_e32 v3, v198, v5
	v_add_f32_e32 v11, v2, v3
	global_load_dwordx4 v[196:199], v[168:169], off offset:-4096 nt
	s_waitcnt vmcnt(15)
	v_mul_f32_e32 v2, v201, v7
	v_mul_f32_e32 v3, v203, v6
	v_fmac_f32_e32 v2, v200, v4
	v_fmac_f32_e32 v3, v202, v5
	v_add_f32_e32 v12, v2, v3
	global_load_dwordx4 v[200:203], v[168:169], off nt
	v_add_co_u32_e32 v168, vcc, 0x16000, v0
	s_nop 1
	v_addc_co_u32_e32 v169, vcc, 0, v1, vcc
	s_waitcnt vmcnt(15)
	v_mul_f32_e32 v2, v205, v7
	v_mul_f32_e32 v3, v207, v6
	v_fmac_f32_e32 v2, v204, v4
	v_fmac_f32_e32 v3, v206, v5
	v_add_f32_e32 v14, v2, v3
	global_load_dwordx4 v[204:207], v[168:169], off offset:-4096 nt
	s_waitcnt vmcnt(15)
	v_mul_f32_e32 v2, v209, v7
	v_mul_f32_e32 v3, v211, v6
	v_fmac_f32_e32 v2, v208, v4
	v_fmac_f32_e32 v3, v210, v5
	v_add_f32_e32 v13, v2, v3
	global_load_dwordx4 v[208:211], v[168:169], off nt
	v_add_co_u32_e32 v168, vcc, 0x18000, v0
	s_nop 1
	v_addc_co_u32_e32 v169, vcc, 0, v1, vcc
	s_waitcnt vmcnt(15)
	v_mul_f32_e32 v2, v213, v7
	v_mul_f32_e32 v3, v215, v6
	v_fmac_f32_e32 v2, v212, v4
	v_fmac_f32_e32 v3, v214, v5
	v_add_f32_e32 v15, v2, v3
	global_load_dwordx4 v[212:215], v[168:169], off offset:-4096 nt
	s_waitcnt vmcnt(15)
	v_mul_f32_e32 v2, v217, v7
	v_mul_f32_e32 v3, v219, v6
	v_fmac_f32_e32 v2, v216, v4
	v_fmac_f32_e32 v3, v218, v5
	v_add_f32_e32 v16, v2, v3
	global_load_dwordx4 v[216:219], v[168:169], off nt
	v_add_co_u32_e32 v168, vcc, 0x1a000, v0
	s_nop 1
	v_addc_co_u32_e32 v169, vcc, 0, v1, vcc
	s_waitcnt vmcnt(15)
	v_mul_f32_e32 v2, v221, v7
	v_mul_f32_e32 v3, v223, v6
	v_fmac_f32_e32 v2, v220, v4
	v_fmac_f32_e32 v3, v222, v5
	v_add_f32_e32 v18, v2, v3
	global_load_dwordx4 v[220:223], v[168:169], off offset:-4096 nt
	s_waitcnt vmcnt(15)
	v_mul_f32_e32 v2, v225, v7
	v_mul_f32_e32 v3, v227, v6
	v_fmac_f32_e32 v2, v224, v4
	v_fmac_f32_e32 v3, v226, v5
	v_add_f32_e32 v17, v2, v3
	global_load_dwordx4 v[224:227], v[168:169], off nt
	v_add_co_u32_e32 v168, vcc, 0x1c000, v0
	s_nop 1
	v_addc_co_u32_e32 v169, vcc, 0, v1, vcc
	s_waitcnt vmcnt(15)
	v_mul_f32_e32 v2, v229, v7
	v_mul_f32_e32 v3, v231, v6
	v_fmac_f32_e32 v2, v228, v4
	v_fmac_f32_e32 v3, v230, v5
	v_add_f32_e32 v20, v2, v3
	global_load_dwordx4 v[228:231], v[168:169], off offset:-4096 nt
	s_waitcnt vmcnt(15)
; __device__ __forceinline__ void p5d_sample_attn(const Params& P, LAS unsigned char* lds, int bid, int G, int tid_in) {
;     ...
; #pragma unroll
;             for (int mi = 0; mi < 32; ++mi) {
;                 const f32x4 kv = __builtin_nontemporal_load((const f32x4*)(kbase + (size_t)mi * (NH * HD)));
;                 d[mi] = (kv[0] * q[0] + kv[1] * q[1]) + (kv[2] * q[2] + kv[3] * q[3]);
;                 if (mi == 15) asm volatile("" ::: "memory");
;             }
; #pragma unroll
;             for (int i = 0; i < 16; ++i) { const bool hi = (lane & 32) != 0; const float snd = hi ? d[i] : d[i + 16], kp = hi ? d[i + 16] : d[i]; d[i] = kp + __shfl_xor(snd, 32); }
	v_mul_f32_e32 v2, v239, v7
	v_mul_f32_e32 v3, v241, v6
	v_fmac_f32_e32 v2, v238, v4
	v_fmac_f32_e32 v3, v240, v5
	v_add_f32_e32 v19, v2, v3
	global_load_dwordx4 v[238:241], v[168:169], off nt
	v_add_co_u32_e32 v168, vcc, 0x1e000, v0
	s_nop 1
	v_addc_co_u32_e32 v169, vcc, 0, v1, vcc
	s_waitcnt vmcnt(15)
	v_mul_f32_e32 v2, v243, v7
	v_mul_f32_e32 v3, v245, v6
	v_fmac_f32_e32 v2, v242, v4
	v_fmac_f32_e32 v3, v244, v5
	v_add_f32_e32 v21, v2, v3
	global_load_dwordx4 v[242:245], v[168:169], off offset:-4096 nt
	s_waitcnt vmcnt(15)
	v_mul_f32_e32 v2, v247, v7
	v_mul_f32_e32 v3, v249, v6
	v_fmac_f32_e32 v2, v246, v4
	v_fmac_f32_e32 v3, v248, v5
	v_add_f32_e32 v22, v2, v3
	global_load_dwordx4 v[246:249], v[168:169], off nt
	v_add_co_u32_e32 v168, vcc, 0x20000, v0
	s_nop 1
	v_addc_co_u32_e32 v169, vcc, 0, v1, vcc
	s_waitcnt vmcnt(15)
	v_mul_f32_e32 v2, v251, v7
	v_mul_f32_e32 v3, v253, v6
	v_fmac_f32_e32 v2, v250, v4
	v_fmac_f32_e32 v3, v252, v5
	v_add_f32_e32 v23, v2, v3
	global_load_dwordx4 v[250:253], v[168:169], off offset:-4096 nt
	v_cmp_lt_i32_e32 vcc, v141, v142
	s_waitcnt vmcnt(15)
	v_mul_f32_e32 v2, v185, v7
	v_mul_f32_e32 v3, v187, v6
	v_fmac_f32_e32 v2, v184, v4
	v_fmac_f32_e32 v3, v186, v5
	v_add_f32_e32 v24, v2, v3
	s_waitcnt vmcnt(14)
	v_mul_f32_e32 v2, v189, v7
	v_mul_f32_e32 v3, v191, v6
	v_fmac_f32_e32 v2, v188, v4
	v_fmac_f32_e32 v3, v190, v5
	v_add_f32_e32 v25, v2, v3
	s_waitcnt vmcnt(13)
	v_mul_f32_e32 v2, v193, v7
	v_mul_f32_e32 v3, v195, v6
	v_fmac_f32_e32 v2, v192, v4
	v_fmac_f32_e32 v3, v194, v5
	v_add_f32_e32 v26, v2, v3
	s_waitcnt vmcnt(12)
	v_mul_f32_e32 v2, v197, v7
	v_mul_f32_e32 v3, v199, v6
	v_fmac_f32_e32 v2, v196, v4
	v_fmac_f32_e32 v3, v198, v5
	v_add_f32_e32 v27, v2, v3
	s_waitcnt vmcnt(11)
	v_mul_f32_e32 v2, v201, v7
	v_mul_f32_e32 v3, v203, v6
	v_fmac_f32_e32 v2, v200, v4
	v_fmac_f32_e32 v3, v202, v5
	v_add_f32_e32 v28, v2, v3
	s_waitcnt vmcnt(10)
	v_mul_f32_e32 v2, v205, v7
	v_mul_f32_e32 v3, v207, v6
	v_fmac_f32_e32 v2, v204, v4
	v_fmac_f32_e32 v3, v206, v5
	v_add_f32_e32 v29, v2, v3
	s_waitcnt vmcnt(9)
	v_mul_f32_e32 v2, v209, v7
	v_mul_f32_e32 v3, v211, v6
	v_fmac_f32_e32 v2, v208, v4
	v_fmac_f32_e32 v3, v210, v5
	v_add_f32_e32 v30, v2, v3
	s_waitcnt vmcnt(8)
	v_mul_f32_e32 v2, v213, v7
	v_mul_f32_e32 v3, v215, v6
	v_fmac_f32_e32 v2, v212, v4
	v_fmac_f32_e32 v3, v214, v5
	v_add_f32_e32 v31, v2, v3
	s_waitcnt vmcnt(7)
	v_mul_f32_e32 v2, v217, v7
	v_mul_f32_e32 v3, v219, v6
	v_fmac_f32_e32 v2, v216, v4
	v_fmac_f32_e32 v3, v218, v5
	v_add_f32_e32 v32, v2, v3
	s_waitcnt vmcnt(6)
	v_mul_f32_e32 v2, v221, v7
	v_mul_f32_e32 v3, v223, v6
	v_fmac_f32_e32 v2, v220, v4
	v_fmac_f32_e32 v3, v222, v5
	v_add_f32_e32 v33, v2, v3
	s_waitcnt vmcnt(5)
	v_mul_f32_e32 v2, v225, v7
	v_mul_f32_e32 v3, v227, v6
	v_fmac_f32_e32 v2, v224, v4
	v_fmac_f32_e32 v3, v226, v5
	v_add_f32_e32 v34, v2, v3
	s_waitcnt vmcnt(4)
	v_mul_f32_e32 v2, v229, v7
	v_mul_f32_e32 v3, v231, v6
	v_fmac_f32_e32 v2, v228, v4
	v_fmac_f32_e32 v3, v230, v5
	v_add_f32_e32 v35, v2, v3
	s_waitcnt vmcnt(3)
	v_mul_f32_e32 v2, v239, v7
	v_mul_f32_e32 v3, v241, v6
	v_fmac_f32_e32 v2, v238, v4
	v_fmac_f32_e32 v3, v240, v5
	v_add_f32_e32 v36, v2, v3
	s_waitcnt vmcnt(2)
	v_mul_f32_e32 v2, v243, v7
	v_mul_f32_e32 v3, v245, v6
	v_fmac_f32_e32 v2, v242, v4
	v_fmac_f32_e32 v3, v244, v5
	v_add_f32_e32 v37, v2, v3
	s_waitcnt vmcnt(1)
	v_mul_f32_e32 v2, v247, v7
	v_mul_f32_e32 v3, v249, v6
	v_fmac_f32_e32 v2, v246, v4
	v_fmac_f32_e32 v3, v248, v5
	v_add_f32_e32 v38, v2, v3
	s_waitcnt vmcnt(0)
	v_mul_f32_e32 v2, v251, v7
	v_mul_f32_e32 v3, v253, v6
	v_fmac_f32_e32 v2, v250, v4
	v_fmac_f32_e32 v3, v252, v5
	v_add_f32_e32 v1, v2, v3
	v_cndmask_b32_e32 v0, v140, v141, vcc
	v_lshlrev_b32_e32 v0, 2, v0
	v_cndmask_b32_e64 v2, v8, v24, s[4:5]
	ds_bpermute_b32 v2, v0, v2
	v_cndmask_b32_e64 v3, v24, v8, s[4:5]
	v_cndmask_b32_e64 v4, v25, v10, s[4:5]
	v_cndmask_b32_e64 v5, v26, v9, s[4:5]
	v_cndmask_b32_e64 v6, v27, v11, s[4:5]
	s_waitcnt lgkmcnt(0)
	v_add_f32_e32 v2, v3, v2
	v_cndmask_b32_e64 v3, v10, v25, s[4:5]
	ds_bpermute_b32 v3, v0, v3
	v_cndmask_b32_e64 v7, v28, v12, s[4:5]
	v_cndmask_b32_e64 v8, v29, v14, s[4:5]
	v_cndmask_b32_e64 v10, v31, v15, s[4:5]
	v_cmp_lt_i32_e32 vcc, v143, v142
	s_waitcnt lgkmcnt(0)
	v_add_f32_e32 v3, v4, v3
	v_cndmask_b32_e64 v4, v9, v26, s[4:5]
	ds_bpermute_b32 v4, v0, v4
	v_cndmask_b32_e64 v9, v30, v13, s[4:5]
	s_waitcnt lgkmcnt(0)
	v_add_f32_e32 v4, v5, v4
	v_cndmask_b32_e64 v5, v11, v27, s[4:5]
	ds_bpermute_b32 v5, v0, v5
	v_cndmask_b32_e64 v11, v32, v16, s[4:5]
	s_waitcnt lgkmcnt(0)
	v_add_f32_e32 v5, v6, v5
	v_cndmask_b32_e64 v6, v12, v28, s[4:5]
	ds_bpermute_b32 v6, v0, v6
	v_cndmask_b32_e64 v12, v33, v18, s[4:5]
	s_waitcnt lgkmcnt(0)
; __device__ __forceinline__ void p5d_sample_attn(const Params& P, LAS unsigned char* lds, int bid, int G, int tid_in) {
;     ...
;             for (int i = 0; i < 16; ++i) { const bool hi = (lane & 32) != 0; const float snd = hi ? d[i] : d[i + 16], kp = hi ? d[i + 16] : d[i]; d[i] = kp + __shfl_xor(snd, 32); }
; #pragma unroll
;             for (int i = 0; i < 8; ++i) { const bool hi = (lane & 16) != 0; const float snd = hi ? d[i] : d[i + 8], kp = hi ? d[i + 8] : d[i]; d[i] = kp + __shfl_xor(snd, 16); }
; #pragma unroll
;             for (int i = 0; i < 4; ++i) { const bool hi = (lane & 8) != 0; const float snd = hi ? d[i] : d[i + 4], kp = hi ? d[i + 4] : d[i]; d[i] = kp + __shfl_xor(snd, 8); }
; #pragma unroll
;             for (int i = 0; i < 2; ++i) { const bool hi = (lane & 4) != 0; const float snd = hi ? d[i] : d[i + 2], kp = hi ? d[i + 2] : d[i]; d[i] = kp + __shfl_xor(snd, 4); }
;             { const bool hi = (lane & 2) != 0; const float snd = hi ? d[0] : d[1], kp = hi ? d[1] : d[0]; d[0] = kp + __shfl_xor(snd, 2); }
;             d[0] += __shfl_xor(d[0], 1);
;             if ((lane & 1) == 0) sS[32 * wave + (lane >> 1)] = d[0] * 0.0625f;
	v_add_f32_e32 v6, v7, v6
	v_cndmask_b32_e64 v7, v14, v29, s[4:5]
	ds_bpermute_b32 v7, v0, v7
	v_cndmask_b32_e64 v14, v35, v20, s[4:5]
	s_waitcnt lgkmcnt(0)
	v_add_f32_e32 v7, v8, v7
	v_cndmask_b32_e64 v8, v13, v30, s[4:5]
	ds_bpermute_b32 v8, v0, v8
	v_cndmask_b32_e64 v13, v34, v17, s[4:5]
	s_waitcnt lgkmcnt(0)
	v_add_f32_e32 v8, v9, v8
	v_cndmask_b32_e64 v9, v15, v31, s[4:5]
	ds_bpermute_b32 v9, v0, v9
	v_cndmask_b32_e64 v15, v36, v19, s[4:5]
	s_waitcnt lgkmcnt(0)
	v_add_f32_e32 v9, v10, v9
	v_cndmask_b32_e64 v10, v16, v32, s[4:5]
	ds_bpermute_b32 v10, v0, v10
	v_cndmask_b32_e64 v16, v37, v21, s[4:5]
	s_waitcnt lgkmcnt(0)
	v_add_f32_e32 v10, v11, v10
	v_cndmask_b32_e64 v11, v18, v33, s[4:5]
	ds_bpermute_b32 v11, v0, v11
	v_cndmask_b32_e64 v18, v2, v10, s[6:7]
	v_cndmask_b32_e64 v2, v10, v2, s[6:7]
	s_waitcnt lgkmcnt(0)
	v_add_f32_e32 v11, v12, v11
	v_cndmask_b32_e64 v12, v17, v34, s[4:5]
	ds_bpermute_b32 v12, v0, v12
	v_cndmask_b32_e64 v17, v38, v22, s[4:5]
	s_waitcnt lgkmcnt(0)
	v_add_f32_e32 v12, v13, v12
	v_cndmask_b32_e64 v13, v20, v35, s[4:5]
	ds_bpermute_b32 v13, v0, v13
	s_waitcnt lgkmcnt(0)
	v_add_f32_e32 v13, v14, v13
	v_cndmask_b32_e64 v14, v19, v36, s[4:5]
	ds_bpermute_b32 v14, v0, v14
	s_waitcnt lgkmcnt(0)
	v_add_f32_e32 v14, v15, v14
	v_cndmask_b32_e64 v15, v21, v37, s[4:5]
	ds_bpermute_b32 v15, v0, v15
	s_waitcnt lgkmcnt(0)
	v_add_f32_e32 v15, v16, v15
	v_cndmask_b32_e64 v16, v22, v38, s[4:5]
	ds_bpermute_b32 v16, v0, v16
	s_waitcnt lgkmcnt(0)
	v_add_f32_e32 v16, v17, v16
	v_cndmask_b32_e64 v17, v23, v1, s[4:5]
	ds_bpermute_b32 v17, v0, v17
	v_cndmask_b32_e64 v1, v1, v23, s[4:5]
	s_waitcnt lgkmcnt(0)
	v_add_f32_e32 v17, v1, v17
	v_cndmask_b32_e32 v1, v140, v143, vcc
	v_lshlrev_b32_e32 v1, 2, v1
	ds_bpermute_b32 v10, v1, v18
	v_cmp_lt_i32_e32 vcc, v144, v142
	s_waitcnt lgkmcnt(0)
	v_add_f32_e32 v10, v2, v10
	v_cndmask_b32_e64 v2, v3, v11, s[6:7]
	ds_bpermute_b32 v2, v1, v2
	v_cndmask_b32_e64 v3, v11, v3, s[6:7]
	s_waitcnt lgkmcnt(0)
	v_add_f32_e32 v3, v3, v2
	v_cndmask_b32_e64 v2, v4, v12, s[6:7]
	ds_bpermute_b32 v2, v1, v2
	v_cndmask_b32_e64 v4, v12, v4, s[6:7]
	s_waitcnt lgkmcnt(0)
	v_add_f32_e32 v4, v4, v2
	v_cndmask_b32_e64 v2, v5, v13, s[6:7]
	ds_bpermute_b32 v2, v1, v2
	v_cndmask_b32_e64 v5, v13, v5, s[6:7]
	s_waitcnt lgkmcnt(0)
	v_add_f32_e32 v5, v5, v2
	v_cndmask_b32_e64 v2, v6, v14, s[6:7]
	ds_bpermute_b32 v2, v1, v2
	v_cndmask_b32_e64 v6, v14, v6, s[6:7]
	s_waitcnt lgkmcnt(0)
	v_add_f32_e32 v6, v6, v2
	v_cndmask_b32_e64 v2, v7, v15, s[6:7]
	ds_bpermute_b32 v2, v1, v2
	v_cndmask_b32_e64 v7, v15, v7, s[6:7]
	v_cndmask_b32_e64 v11, v10, v6, s[8:9]
	v_cndmask_b32_e64 v6, v6, v10, s[8:9]
	s_waitcnt lgkmcnt(0)
	v_add_f32_e32 v7, v7, v2
	v_cndmask_b32_e64 v2, v8, v16, s[6:7]
	ds_bpermute_b32 v2, v1, v2
	v_cndmask_b32_e64 v8, v16, v8, s[6:7]
	s_waitcnt lgkmcnt(0)
	v_add_f32_e32 v8, v8, v2
	v_cndmask_b32_e64 v2, v9, v17, s[6:7]
	ds_bpermute_b32 v2, v1, v2
	v_cndmask_b32_e64 v9, v17, v9, s[6:7]
	s_waitcnt lgkmcnt(0)
	v_add_f32_e32 v9, v9, v2
	v_cndmask_b32_e32 v2, v140, v144, vcc
	v_lshlrev_b32_e32 v2, 2, v2
	ds_bpermute_b32 v10, v2, v11
	v_cmp_lt_i32_e32 vcc, v145, v142
	s_waitcnt lgkmcnt(0)
	v_add_f32_e32 v6, v6, v10
	v_cndmask_b32_e64 v10, v3, v7, s[8:9]
	v_cndmask_b32_e64 v3, v7, v3, s[8:9]
	ds_bpermute_b32 v7, v2, v10
	s_waitcnt lgkmcnt(0)
	v_add_f32_e32 v7, v3, v7
	v_cndmask_b32_e64 v3, v4, v8, s[8:9]
	ds_bpermute_b32 v3, v2, v3
	v_cndmask_b32_e64 v4, v8, v4, s[8:9]
	s_waitcnt lgkmcnt(0)
	v_add_f32_e32 v4, v4, v3
	v_cndmask_b32_e64 v3, v5, v9, s[8:9]
	ds_bpermute_b32 v3, v2, v3
	v_cndmask_b32_e64 v5, v9, v5, s[8:9]
	v_cndmask_b32_e64 v8, v6, v4, s[10:11]
	v_cndmask_b32_e64 v4, v4, v6, s[10:11]
	s_waitcnt lgkmcnt(0)
	v_add_f32_e32 v5, v5, v3
	v_cndmask_b32_e32 v3, v140, v145, vcc
	v_lshlrev_b32_e32 v3, 2, v3
	ds_bpermute_b32 v6, v3, v8
	v_cmp_lt_i32_e32 vcc, v146, v142
	s_waitcnt lgkmcnt(0)
	v_add_f32_e32 v4, v4, v6
	v_cndmask_b32_e64 v6, v7, v5, s[10:11]
	ds_bpermute_b32 v6, v3, v6
	v_cndmask_b32_e64 v5, v5, v7, s[10:11]
	s_waitcnt lgkmcnt(0)
	v_add_f32_e32 v5, v5, v6
	v_cndmask_b32_e64 v6, v4, v5, s[12:13]
	v_cndmask_b32_e64 v5, v5, v4, s[12:13]
	v_cndmask_b32_e32 v4, v140, v146, vcc
	v_lshlrev_b32_e32 v4, 2, v4
	ds_bpermute_b32 v6, v4, v6
	v_cmp_lt_i32_e32 vcc, v147, v142
	s_waitcnt lgkmcnt(0)
	v_add_f32_e32 v6, v5, v6
	v_cndmask_b32_e32 v5, v140, v147, vcc
	v_lshlrev_b32_e32 v5, 2, v5
	ds_bpermute_b32 v7, v5, v6
	s_and_saveexec_b64 s[18:19], s[14:15]
	s_cbranch_execz .LBB0_639
	s_waitcnt lgkmcnt(0)
	v_add_f32_e32 v6, v6, v7
	v_mul_f32_e32 v6, 0x3d800000, v6
	ds_write_b32 v136, v6
